# v63: barrier leader no longer waits for the TOPGEN atomic before releasing its own XCD
# baseline (speedup 1.0000x reference)
.LBB0_142:
	s_or_b64 exec, exec, s[6:7]
	s_mov_b64 s[6:7], exec
	v_mbcnt_lo_u32_b32 v1, s6, 0
	v_mbcnt_hi_u32_b32 v1, s7, v1
	v_cmp_eq_u32_e32 vcc, 0, v1
	s_and_saveexec_b64 s[8:9], vcc
	s_cbranch_execz .LBB0_144
	s_bcnt1_i32_b64 s6, s[6:7]
	v_mov_b32_e32 v1, 0x2000
	v_mov_b32_e32 v2, s6
	global_atomic_add v1, v2, s[4:5] offset:1024

.LBB0_625:
	s_or_b64 exec, exec, s[4:5]
	s_mov_b64 s[4:5], exec
	v_mbcnt_lo_u32_b32 v1, s4, 0
	v_mbcnt_hi_u32_b32 v1, s5, v1
	v_cmp_eq_u32_e32 vcc, 0, v1
	s_and_saveexec_b64 s[6:7], vcc
	s_cbranch_execz .LBB0_627
	s_bcnt1_i32_b64 s4, s[4:5]
	v_mov_b32_e32 v1, 0x2000
	v_mov_b32_e32 v2, s4
	global_atomic_add v1, v2, s[2:3] offset:1024

.LBB0_1602:
	s_or_b64 exec, exec, s[6:7]
	s_mov_b64 s[6:7], exec
	v_mbcnt_lo_u32_b32 v1, s6, 0
	v_mbcnt_hi_u32_b32 v1, s7, v1
	v_cmp_eq_u32_e32 vcc, 0, v1
	s_and_saveexec_b64 s[8:9], vcc
	s_cbranch_execz .LBB0_1604
	s_bcnt1_i32_b64 s6, s[6:7]
	v_mov_b32_e32 v1, 0x2000
	v_mov_b32_e32 v2, s6
	global_atomic_add v1, v2, s[2:3] offset:1024
